# v61-based: P5 SSP loads of 6 row blocks issued at the start of the last K-loop iteration (after its first barrier), last-iteration waits 14/14
# baseline (speedup 1.0000x reference)
; #define PG8_STAGE(bufoff, gbase, voff) do { _Pragma("unroll") for (int _i = 0; _i < 2; ++_i) \
;         __builtin_amdgcn_global_load_lds((const unsigned*)((const char*)(gbase) + (voff)[_i]), (PG8_LAS unsigned*)(lds + (bufoff) + ldsw + _i * 8192), 16, 0, 0); } while (0)
; #define PG8_LDA(dst, b, h) do { _Pragma("unroll") for (int m = 0; m < 4; ++m) _Pragma("unroll") for (int k = 0; k < 2; ++k) dst[m][k] = *(const PG8_LAS bf16x8*)(lds + PG8_SA(b, h) + aoff + m * 2048 + k * 1024); } while (0)
; #define PG8_MMA(ai, bj, At, Bt) do { __builtin_amdgcn_s_setprio(1); _Pragma("unroll") for (int m = 0; m < 4; ++m) _Pragma("unroll") for (int n = 0; n < 2; ++n) _Pragma("unroll") for (int k = 0; k < 2; ++k) \
;         acc[ai][bj][m][n] = __builtin_amdgcn_mfma_f32_16x16x32_bf16(Bt[n][k], At[m][k], acc[ai][bj][m][n], 0, 0, 0); __builtin_amdgcn_s_setprio(0); } while (0)
; #define PG8_WAIT_V(n) asm volatile("s_waitcnt vmcnt(" #n ")" ::: "memory")
; #define PG8_WAIT_L(n) asm volatile("s_waitcnt lgkmcnt(" #n ")" ::: "memory")
; #define PG8_BAR __builtin_amdgcn_s_barrier()
; #define PG8_SCHED __builtin_amdgcn_sched_barrier(0)
; template <class Epi, class Sched, bool ALIGN_EPI = false, bool SP2 = false>
; __device__ __forceinline__ void gemm_phase(PG8_LAS unsigned char* lds, const Gemm g, const Sched& S, const Epi& E) {
;     ...
;             PG8_WAIT_V(8); PG8_WAIT_L(0); PG8_BAR; PG8_MMA(0, 0, At, B0); PG8_MMA(0, 1, At, B1); PG8_BAR; PG8_SCHED;
;             PG8_LDA(At, 0, 1); PG8_STAGE(PG8_SB(0, 0), b2, voffB); PG8_STAGE(PG8_SB(0, 1), b2 + hstep, voffB); PG8_STAGE(PG8_SA(0, 0), a2, voffA);
;             PG8_WAIT_V(8); PG8_WAIT_L(0); PG8_BAR; PG8_MMA(1, 0, At, B0); PG8_MMA(1, 1, At, B1); PG8_BAR; PG8_SCHED;
.Lrw_P5_0:
	s_waitcnt vmcnt(24)
.Lrj_P5_0:
	s_waitcnt lgkmcnt(0)
	s_barrier
	s_cmp_eq_u32 s65, 12
	s_cbranch_scc0 .Lessp_skip
	v_lshl_add_u32 v252, s28, 8, v148
	v_bfe_u32 v253, v226, 4, 2
	v_lshlrev_b32_e32 v252, 6, v252
	v_lshl_add_u32 v252, v253, 4, v252
	v_add_u32_e32 v253, 0x2000, v252
	global_load_dwordx4 v[228:231], v252, s[12:13]
	global_load_dwordx4 v[232:235], v252, s[12:13] offset:1024
	global_load_dwordx4 v[236:239], v252, s[12:13] offset:2048
	global_load_dwordx4 v[240:243], v252, s[12:13] offset:3072
	global_load_dwordx4 v[244:247], v253, s[12:13]
	global_load_dwordx4 v[248:251], v253, s[12:13] offset:1024
.Lessp_skip:
	s_setprio 1
	s_waitcnt lgkmcnt(0)
	v_mfma_f32_16x16x32_bf16 v[124:127], v[144:147], v[184:187], v[124:127]
	v_mfma_f32_16x16x32_bf16 v[120:123], v[160:163], v[184:187], v[120:123]
	v_mfma_f32_16x16x32_bf16 v[108:111], v[144:147], v[192:195], v[108:111]
	v_mfma_f32_16x16x32_bf16 v[104:107], v[160:163], v[192:195], v[104:107]
	v_mfma_f32_16x16x32_bf16 v[92:95], v[144:147], v[200:203], v[92:95]
	v_mfma_f32_16x16x32_bf16 v[88:91], v[160:163], v[200:203], v[88:91]
	v_mfma_f32_16x16x32_bf16 v[76:79], v[144:147], v[208:211], v[76:79]
	v_mfma_f32_16x16x32_bf16 v[72:75], v[160:163], v[208:211], v[72:75]
	v_mfma_f32_16x16x32_bf16 v[124:127], v[156:159], v[188:191], v[124:127]
	v_mfma_f32_16x16x32_bf16 v[120:123], v[164:167], v[188:191], v[120:123]
	v_mfma_f32_16x16x32_bf16 v[108:111], v[156:159], v[196:199], v[108:111]
	v_mfma_f32_16x16x32_bf16 v[104:107], v[164:167], v[196:199], v[104:107]
	v_mfma_f32_16x16x32_bf16 v[92:95], v[156:159], v[204:207], v[92:95]
	v_mfma_f32_16x16x32_bf16 v[88:91], v[164:167], v[204:207], v[88:91]
	v_mfma_f32_16x16x32_bf16 v[76:79], v[156:159], v[212:215], v[76:79]
	v_mfma_f32_16x16x32_bf16 v[72:75], v[164:167], v[212:215], v[72:75]
	s_setprio 0
	s_setprio 1
	v_mfma_f32_16x16x32_bf16 v[116:119], v[168:171], v[184:187], v[116:119]
	v_mfma_f32_16x16x32_bf16 v[112:115], v[176:179], v[184:187], v[112:115]
	v_mfma_f32_16x16x32_bf16 v[100:103], v[168:171], v[192:195], v[100:103]
	v_mfma_f32_16x16x32_bf16 v[96:99], v[176:179], v[192:195], v[96:99]
	v_mfma_f32_16x16x32_bf16 v[84:87], v[168:171], v[200:203], v[84:87]
	v_mfma_f32_16x16x32_bf16 v[80:83], v[176:179], v[200:203], v[80:83]
	v_mfma_f32_16x16x32_bf16 v[68:71], v[168:171], v[208:211], v[68:71]
	v_mfma_f32_16x16x32_bf16 v[64:67], v[176:179], v[208:211], v[64:67]
	v_mfma_f32_16x16x32_bf16 v[116:119], v[172:175], v[188:191], v[116:119]
	v_mfma_f32_16x16x32_bf16 v[112:115], v[180:183], v[188:191], v[112:115]
	v_mfma_f32_16x16x32_bf16 v[100:103], v[172:175], v[196:199], v[100:103]
	v_mfma_f32_16x16x32_bf16 v[96:99], v[180:183], v[196:199], v[96:99]
	v_mfma_f32_16x16x32_bf16 v[84:87], v[172:175], v[204:207], v[84:87]
	v_mfma_f32_16x16x32_bf16 v[80:83], v[180:183], v[204:207], v[80:83]
	v_mfma_f32_16x16x32_bf16 v[68:71], v[172:175], v[212:215], v[68:71]
	v_mfma_f32_16x16x32_bf16 v[64:67], v[180:183], v[212:215], v[64:67]
	s_setprio 0
	s_barrier
	s_add_i32 s66, s52, s39
	v_lshl_add_u64 v[216:217], s[34:35], 0, v[132:133]
	s_mov_b32 m0, s66
	ds_read_b128 v[184:187], v153 offset:16384
	ds_read_b128 v[188:191], v153 offset:17408
	ds_read_b128 v[192:195], v153 offset:18432
	ds_read_b128 v[196:199], v153 offset:19456
	ds_read_b128 v[200:203], v153 offset:20480
	ds_read_b128 v[204:207], v153 offset:21504
	ds_read_b128 v[208:211], v153 offset:22528
	ds_read_b128 v[212:215], v153 offset:23552
	global_load_lds_dwordx4 v[216:217], off
	s_add_i32 m0, s66, 0x2000
	s_add_u32 s66, s34, 0x40000
	v_lshl_add_u64 v[218:219], s[34:35], 0, v[128:129]
	s_addc_u32 s67, s35, 0
	s_add_i32 s68, s53, s39
	global_load_lds_dwordx4 v[218:219], off
	v_lshl_add_u64 v[220:221], s[66:67], 0, v[132:133]
	s_mov_b32 m0, s68
	v_lshl_add_u64 v[222:223], s[36:37], 0, v[130:131]
	global_load_lds_dwordx4 v[220:221], off
	v_lshl_add_u64 v[220:221], s[66:67], 0, v[128:129]
	s_add_i32 m0, s68, 0x2000
	s_nop 0
	global_load_lds_dwordx4 v[220:221], off
	v_lshl_add_u64 v[220:221], s[36:37], 0, v[134:135]
	s_mov_b32 m0, s29
	s_nop 0
	global_load_lds_dwordx4 v[220:221], off
	s_mov_b32 m0, s42
	s_nop 0
	global_load_lds_dwordx4 v[222:223], off
	s_cmp_eq_u32 s99, 1
	s_cbranch_scc1 .Lrw_P5_1
	s_cmp_eq_u32 s65, 12
	s_cbranch_scc1 .Lw2l_P5
	s_waitcnt vmcnt(8)
	s_branch .Lrj_P5_1
.Lw2l_P5:
	s_waitcnt vmcnt(14)
	s_branch .Lrj_P5_1

; #define PG8_STAGE(bufoff, gbase, voff) do { _Pragma("unroll") for (int _i = 0; _i < 2; ++_i) \
;         __builtin_amdgcn_global_load_lds((const unsigned*)((const char*)(gbase) + (voff)[_i]), (PG8_LAS unsigned*)(lds + (bufoff) + ldsw + _i * 8192), 16, 0, 0); } while (0)
; #define PG8_LDA(dst, b, h) do { _Pragma("unroll") for (int m = 0; m < 4; ++m) _Pragma("unroll") for (int k = 0; k < 2; ++k) dst[m][k] = *(const PG8_LAS bf16x8*)(lds + PG8_SA(b, h) + aoff + m * 2048 + k * 1024); } while (0)
; #define PG8_LDB(dst, b, h) do { _Pragma("unroll") for (int n = 0; n < 2; ++n) _Pragma("unroll") for (int k = 0; k < 2; ++k) dst[n][k] = *(const PG8_LAS bf16x8*)(lds + PG8_SB(b, h) + boff + n * 2048 + k * 1024); } while (0)
; #define PG8_MMA(ai, bj, At, Bt) do { __builtin_amdgcn_s_setprio(1); _Pragma("unroll") for (int m = 0; m < 4; ++m) _Pragma("unroll") for (int n = 0; n < 2; ++n) _Pragma("unroll") for (int k = 0; k < 2; ++k) \
;         acc[ai][bj][m][n] = __builtin_amdgcn_mfma_f32_16x16x32_bf16(Bt[n][k], At[m][k], acc[ai][bj][m][n], 0, 0, 0); __builtin_amdgcn_s_setprio(0); } while (0)
; #define PG8_WAIT_V(n) asm volatile("s_waitcnt vmcnt(" #n ")" ::: "memory")
; #define PG8_WAIT_L(n) asm volatile("s_waitcnt lgkmcnt(" #n ")" ::: "memory")
; #define PG8_BAR __builtin_amdgcn_s_barrier()
; #define PG8_SCHED __builtin_amdgcn_sched_barrier(0)
; template <class Epi, class Sched, bool ALIGN_EPI = false, bool SP2 = false>
; __device__ __forceinline__ void gemm_phase(PG8_LAS unsigned char* lds, const Gemm g, const Sched& S, const Epi& E) {
;     ...
;             PG8_WAIT_V(8); PG8_WAIT_L(0); PG8_BAR; PG8_MMA(1, 0, At, B0); PG8_MMA(1, 1, At, B1); PG8_BAR; PG8_SCHED;
;             PG8_LDB(B0, 1, 0); PG8_LDB(B1, 1, 1); PG8_SCHED; PG8_LDA(At, 1, 0); PG8_STAGE(PG8_SA(0, 1), a2 + hstep, voffA);
.Lrj_P5_1:
	s_waitcnt lgkmcnt(0)
	s_barrier
	s_setprio 1
	s_waitcnt lgkmcnt(0)
	v_mfma_f32_16x16x32_bf16 v[60:63], v[144:147], v[184:187], v[60:63]
	v_mfma_f32_16x16x32_bf16 v[56:59], v[160:163], v[184:187], v[56:59]
	v_mfma_f32_16x16x32_bf16 v[44:47], v[144:147], v[192:195], v[44:47]
	v_mfma_f32_16x16x32_bf16 v[40:43], v[160:163], v[192:195], v[40:43]
	v_mfma_f32_16x16x32_bf16 v[28:31], v[144:147], v[200:203], v[28:31]
	v_mfma_f32_16x16x32_bf16 v[24:27], v[160:163], v[200:203], v[24:27]
	v_mfma_f32_16x16x32_bf16 v[12:15], v[144:147], v[208:211], v[12:15]
	v_mfma_f32_16x16x32_bf16 v[8:11], v[160:163], v[208:211], v[8:11]
	v_mfma_f32_16x16x32_bf16 v[60:63], v[156:159], v[188:191], v[60:63]
	v_mfma_f32_16x16x32_bf16 v[56:59], v[164:167], v[188:191], v[56:59]
	v_mfma_f32_16x16x32_bf16 v[44:47], v[156:159], v[196:199], v[44:47]
	v_mfma_f32_16x16x32_bf16 v[40:43], v[164:167], v[196:199], v[40:43]
	v_mfma_f32_16x16x32_bf16 v[28:31], v[156:159], v[204:207], v[28:31]
	v_mfma_f32_16x16x32_bf16 v[24:27], v[164:167], v[204:207], v[24:27]
	v_mfma_f32_16x16x32_bf16 v[12:15], v[156:159], v[212:215], v[12:15]
	v_mfma_f32_16x16x32_bf16 v[8:11], v[164:167], v[212:215], v[8:11]
	s_setprio 0
	s_setprio 1
	v_mfma_f32_16x16x32_bf16 v[52:55], v[168:171], v[184:187], v[52:55]
	v_mfma_f32_16x16x32_bf16 v[48:51], v[176:179], v[184:187], v[48:51]
	v_mfma_f32_16x16x32_bf16 v[36:39], v[168:171], v[192:195], v[36:39]
	v_mfma_f32_16x16x32_bf16 v[32:35], v[176:179], v[192:195], v[32:35]
	v_mfma_f32_16x16x32_bf16 v[20:23], v[168:171], v[200:203], v[20:23]
	v_mfma_f32_16x16x32_bf16 v[16:19], v[176:179], v[200:203], v[16:19]
	v_mfma_f32_16x16x32_bf16 v[4:7], v[168:171], v[208:211], v[4:7]
	v_mfma_f32_16x16x32_bf16 v[0:3], v[176:179], v[208:211], v[0:3]
	v_mfma_f32_16x16x32_bf16 v[52:55], v[172:175], v[188:191], v[52:55]
	v_mfma_f32_16x16x32_bf16 v[48:51], v[180:183], v[188:191], v[48:51]
	v_mfma_f32_16x16x32_bf16 v[36:39], v[172:175], v[196:199], v[36:39]
	v_mfma_f32_16x16x32_bf16 v[32:35], v[180:183], v[196:199], v[32:35]
	v_mfma_f32_16x16x32_bf16 v[20:23], v[172:175], v[204:207], v[20:23]
	v_mfma_f32_16x16x32_bf16 v[16:19], v[180:183], v[204:207], v[16:19]
	v_mfma_f32_16x16x32_bf16 v[4:7], v[172:175], v[212:215], v[4:7]
	v_mfma_f32_16x16x32_bf16 v[0:3], v[180:183], v[212:215], v[0:3]
	s_setprio 0
	s_barrier
	s_add_i32 s66, 0, 0x18000
	v_add_u32_e32 v155, s66, v149
	s_add_i32 s67, 0, 0x1c000
	ds_read_b128 v[144:147], v155
	ds_read_b128 v[156:159], v155 offset:1024
	ds_read_b128 v[160:163], v155 offset:2048
	ds_read_b128 v[164:167], v155 offset:3072
	v_add_u32_e32 v155, s67, v149
	ds_read_b128 v[168:171], v155
	ds_read_b128 v[172:175], v155 offset:1024
	ds_read_b128 v[176:179], v155 offset:2048
	ds_read_b128 v[180:183], v155 offset:3072
	s_add_u32 s36, s36, 0x40000
	s_addc_u32 s37, s37, 0
	s_mov_b32 m0, s43
	v_lshl_add_u64 v[224:225], s[36:37], 0, v[134:135]
	ds_read_b128 v[184:187], v153 offset:32768
	ds_read_b128 v[188:191], v153 offset:33792
	ds_read_b128 v[192:195], v153 offset:34816
	ds_read_b128 v[196:199], v153 offset:35840
	ds_read_b128 v[200:203], v153 offset:36864
	ds_read_b128 v[204:207], v153 offset:37888
	ds_read_b128 v[208:211], v153 offset:38912
	ds_read_b128 v[212:215], v153 offset:39936
	global_load_lds_dwordx4 v[224:225], off
	v_lshl_add_u64 v[224:225], s[36:37], 0, v[130:131]
	s_mov_b32 m0, s46
	s_nop 0
	global_load_lds_dwordx4 v[224:225], off
	s_cmp_eq_u32 s65, 12
	s_cbranch_scc1 .Lw3l_P5
	s_waitcnt vmcnt(8)
	s_branch .Lw3d_P5

; #define PG8_STAGE(bufoff, gbase, voff) do { _Pragma("unroll") for (int _i = 0; _i < 2; ++_i) \
;         __builtin_amdgcn_global_load_lds((const unsigned*)((const char*)(gbase) + (voff)[_i]), (PG8_LAS unsigned*)(lds + (bufoff) + ldsw + _i * 8192), 16, 0, 0); } while (0)
; #define PG8_LDA(dst, b, h) do { _Pragma("unroll") for (int m = 0; m < 4; ++m) _Pragma("unroll") for (int k = 0; k < 2; ++k) dst[m][k] = *(const PG8_LAS bf16x8*)(lds + PG8_SA(b, h) + aoff + m * 2048 + k * 1024); } while (0)
; #define PG8_MMA(ai, bj, At, Bt) do { __builtin_amdgcn_s_setprio(1); _Pragma("unroll") for (int m = 0; m < 4; ++m) _Pragma("unroll") for (int n = 0; n < 2; ++n) _Pragma("unroll") for (int k = 0; k < 2; ++k) \
;         acc[ai][bj][m][n] = __builtin_amdgcn_mfma_f32_16x16x32_bf16(Bt[n][k], At[m][k], acc[ai][bj][m][n], 0, 0, 0); __builtin_amdgcn_s_setprio(0); } while (0)
; #define PG8_WAIT_V(n) asm volatile("s_waitcnt vmcnt(" #n ")" ::: "memory")
; #define PG8_WAIT_L(n) asm volatile("s_waitcnt lgkmcnt(" #n ")" ::: "memory")
; #define PG8_BAR __builtin_amdgcn_s_barrier()
; #define PG8_SCHED __builtin_amdgcn_sched_barrier(0)
; template <class Epi, class Sched, bool ALIGN_EPI = false, bool SP2 = false>
; __device__ __forceinline__ void gemm_phase(PG8_LAS unsigned char* lds, const Gemm g, const Sched& S, const Epi& E) {
;     ...
;             PG8_WAIT_V(8); PG8_WAIT_L(0); PG8_BAR; PG8_MMA(0, 0, At, B0); PG8_MMA(0, 1, At, B1); PG8_BAR; PG8_SCHED;
;             PG8_LDA(At, 1, 1); PG8_STAGE(PG8_SB(1, 0), b3, voffB); PG8_STAGE(PG8_SB(1, 1), b3 + hstep, voffB); PG8_STAGE(PG8_SA(1, 0), a3, voffA);
;             PG8_WAIT_V(8); PG8_WAIT_L(0); PG8_BAR; PG8_MMA(1, 0, At, B0); PG8_MMA(1, 1, At, B1); PG8_BAR; PG8_SCHED;
;     __device__ __forceinline__ void operator()(const f32x4 (&acc)[2][2][4][2], const Unit& u, int wr, int wc, int fr, int fq) const {
;     ...
;             for (int m = 0; m < 4; ++m) { const int row = rbase + ai * 128 + m * 16; const f32x4* sp = (const f32x4*)(SSP + (size_t)row * 16);
;                 const f32x4 s4 = (sp[0] + sp[1]) + (sp[2] + sp[3]); const float rstd = __builtin_amdgcn_rsqf(((s4[0] + s4[1]) + (s4[2] + s4[3])) * (1.0f / 1024.0f) + EPS);
.Lw3d_P5:
	s_waitcnt lgkmcnt(0)
	s_barrier
	s_setprio 1
	s_waitcnt lgkmcnt(0)
	v_mfma_f32_16x16x32_bf16 v[124:127], v[144:147], v[184:187], v[124:127]
	v_mfma_f32_16x16x32_bf16 v[120:123], v[160:163], v[184:187], v[120:123]
	v_mfma_f32_16x16x32_bf16 v[108:111], v[144:147], v[192:195], v[108:111]
	v_mfma_f32_16x16x32_bf16 v[104:107], v[160:163], v[192:195], v[104:107]
	v_mfma_f32_16x16x32_bf16 v[92:95], v[144:147], v[200:203], v[92:95]
	v_mfma_f32_16x16x32_bf16 v[88:91], v[160:163], v[200:203], v[88:91]
	v_mfma_f32_16x16x32_bf16 v[76:79], v[144:147], v[208:211], v[76:79]
	v_mfma_f32_16x16x32_bf16 v[72:75], v[160:163], v[208:211], v[72:75]
	v_mfma_f32_16x16x32_bf16 v[124:127], v[156:159], v[188:191], v[124:127]
	v_mfma_f32_16x16x32_bf16 v[120:123], v[164:167], v[188:191], v[120:123]
	v_mfma_f32_16x16x32_bf16 v[108:111], v[156:159], v[196:199], v[108:111]
	v_mfma_f32_16x16x32_bf16 v[104:107], v[164:167], v[196:199], v[104:107]
	v_mfma_f32_16x16x32_bf16 v[92:95], v[156:159], v[204:207], v[92:95]
	v_mfma_f32_16x16x32_bf16 v[88:91], v[164:167], v[204:207], v[88:91]
	v_mfma_f32_16x16x32_bf16 v[76:79], v[156:159], v[212:215], v[76:79]
	v_mfma_f32_16x16x32_bf16 v[72:75], v[164:167], v[212:215], v[72:75]
	s_setprio 0
	s_setprio 1
	v_mfma_f32_16x16x32_bf16 v[116:119], v[168:171], v[184:187], v[116:119]
	v_mfma_f32_16x16x32_bf16 v[112:115], v[176:179], v[184:187], v[112:115]
	v_mfma_f32_16x16x32_bf16 v[100:103], v[168:171], v[192:195], v[100:103]
	v_mfma_f32_16x16x32_bf16 v[96:99], v[176:179], v[192:195], v[96:99]
	v_mfma_f32_16x16x32_bf16 v[84:87], v[168:171], v[200:203], v[84:87]
	v_mfma_f32_16x16x32_bf16 v[80:83], v[176:179], v[200:203], v[80:83]
	v_mfma_f32_16x16x32_bf16 v[68:71], v[168:171], v[208:211], v[68:71]
	v_mfma_f32_16x16x32_bf16 v[64:67], v[176:179], v[208:211], v[64:67]
	v_mfma_f32_16x16x32_bf16 v[116:119], v[172:175], v[188:191], v[116:119]
	v_mfma_f32_16x16x32_bf16 v[112:115], v[180:183], v[188:191], v[112:115]
	v_mfma_f32_16x16x32_bf16 v[100:103], v[172:175], v[196:199], v[100:103]
	v_mfma_f32_16x16x32_bf16 v[96:99], v[180:183], v[196:199], v[96:99]
	v_mfma_f32_16x16x32_bf16 v[84:87], v[172:175], v[204:207], v[84:87]
	v_mfma_f32_16x16x32_bf16 v[80:83], v[180:183], v[204:207], v[80:83]
	v_mfma_f32_16x16x32_bf16 v[68:71], v[172:175], v[212:215], v[68:71]
	v_mfma_f32_16x16x32_bf16 v[64:67], v[180:183], v[212:215], v[64:67]
	s_setprio 0
	s_barrier
	s_add_i32 s36, s66, s39
	v_lshl_add_u64 v[216:217], v[216:217], 0, s[14:15]
	s_mov_b32 m0, s36
	ds_read_b128 v[184:187], v153 offset:49152
	ds_read_b128 v[188:191], v153 offset:50176
	ds_read_b128 v[192:195], v153 offset:51200
	ds_read_b128 v[196:199], v153 offset:52224
	ds_read_b128 v[200:203], v153 offset:53248
	ds_read_b128 v[204:207], v153 offset:54272
	ds_read_b128 v[208:211], v153 offset:55296
	ds_read_b128 v[212:215], v153 offset:56320
	global_load_lds_dwordx4 v[216:217], off
	s_add_i32 m0, s36, 0x2000
	s_add_u32 s34, s34, 0x40080
	v_lshl_add_u64 v[216:217], v[218:219], 0, s[14:15]
	s_addc_u32 s35, s35, 0
	s_add_i32 s36, s67, s39
	global_load_lds_dwordx4 v[216:217], off
	v_lshl_add_u64 v[216:217], s[34:35], 0, v[132:133]
	s_mov_b32 m0, s36
	s_nop 0
	global_load_lds_dwordx4 v[216:217], off
	v_lshl_add_u64 v[216:217], s[34:35], 0, v[128:129]
	s_add_i32 m0, s36, 0x2000
	s_nop 0
	global_load_lds_dwordx4 v[216:217], off
	v_lshl_add_u64 v[216:217], v[220:221], 0, s[14:15]
	s_mov_b32 m0, s49
	s_nop 0
	global_load_lds_dwordx4 v[216:217], off
	v_lshl_add_u64 v[216:217], v[222:223], 0, s[14:15]
	s_mov_b32 m0, s50
	s_nop 0
	global_load_lds_dwordx4 v[216:217], off
	s_waitcnt vmcnt(8)
	s_waitcnt lgkmcnt(0)
	s_barrier
	s_setprio 1
	s_waitcnt lgkmcnt(0)
	v_mfma_f32_16x16x32_bf16 v[60:63], v[144:147], v[184:187], v[60:63]
	v_mfma_f32_16x16x32_bf16 v[56:59], v[160:163], v[184:187], v[56:59]
	v_mfma_f32_16x16x32_bf16 v[44:47], v[144:147], v[192:195], v[44:47]
	v_mfma_f32_16x16x32_bf16 v[40:43], v[160:163], v[192:195], v[40:43]
	v_mfma_f32_16x16x32_bf16 v[28:31], v[144:147], v[200:203], v[28:31]
	v_mfma_f32_16x16x32_bf16 v[24:27], v[160:163], v[200:203], v[24:27]
	v_mfma_f32_16x16x32_bf16 v[12:15], v[144:147], v[208:211], v[12:15]
	v_mfma_f32_16x16x32_bf16 v[8:11], v[160:163], v[208:211], v[8:11]
	v_mfma_f32_16x16x32_bf16 v[60:63], v[156:159], v[188:191], v[60:63]
	v_mfma_f32_16x16x32_bf16 v[56:59], v[164:167], v[188:191], v[56:59]
	v_mfma_f32_16x16x32_bf16 v[44:47], v[156:159], v[196:199], v[44:47]
	v_mfma_f32_16x16x32_bf16 v[40:43], v[164:167], v[196:199], v[40:43]
	v_mfma_f32_16x16x32_bf16 v[28:31], v[156:159], v[204:207], v[28:31]
	v_mfma_f32_16x16x32_bf16 v[24:27], v[164:167], v[204:207], v[24:27]
	v_mfma_f32_16x16x32_bf16 v[12:15], v[156:159], v[212:215], v[12:15]
	v_mfma_f32_16x16x32_bf16 v[8:11], v[164:167], v[212:215], v[8:11]
	s_setprio 0
	s_setprio 1
	v_mfma_f32_16x16x32_bf16 v[52:55], v[168:171], v[184:187], v[52:55]
	v_mfma_f32_16x16x32_bf16 v[48:51], v[176:179], v[184:187], v[48:51]
	v_mfma_f32_16x16x32_bf16 v[36:39], v[168:171], v[192:195], v[36:39]
	v_mfma_f32_16x16x32_bf16 v[32:35], v[176:179], v[192:195], v[32:35]
	v_mfma_f32_16x16x32_bf16 v[20:23], v[168:171], v[200:203], v[20:23]
	v_mfma_f32_16x16x32_bf16 v[16:19], v[176:179], v[200:203], v[16:19]
	v_mfma_f32_16x16x32_bf16 v[4:7], v[168:171], v[208:211], v[4:7]
	v_mfma_f32_16x16x32_bf16 v[0:3], v[176:179], v[208:211], v[0:3]
	v_mfma_f32_16x16x32_bf16 v[52:55], v[172:175], v[188:191], v[52:55]
	v_mfma_f32_16x16x32_bf16 v[48:51], v[180:183], v[188:191], v[48:51]
	v_mfma_f32_16x16x32_bf16 v[36:39], v[172:175], v[196:199], v[36:39]
	v_mfma_f32_16x16x32_bf16 v[32:35], v[180:183], v[196:199], v[32:35]
	v_mfma_f32_16x16x32_bf16 v[20:23], v[172:175], v[204:207], v[20:23]
	v_mfma_f32_16x16x32_bf16 v[16:19], v[180:183], v[204:207], v[16:19]
	v_mfma_f32_16x16x32_bf16 v[4:7], v[172:175], v[212:215], v[4:7]
	v_mfma_f32_16x16x32_bf16 v[0:3], v[180:183], v[212:215], v[0:3]
	s_setprio 0
	s_barrier
	s_mov_b32 s99, 0
	s_add_i32 s65, s65, 2
	s_add_u32 s30, s30, 0x100
	s_addc_u32 s31, s31, 0
	s_add_u32 s63, s63, 0x100
	s_addc_u32 s64, s64, 0
	s_cmp_gt_u32 s65, 13
	s_cbranch_scc0 .LBB0_1540
	v_lshl_add_u32 v146, s28, 8, v148
	v_ashrrev_i32_e32 v147, 31, v146
	v_lshlrev_b64 v[144:145], 6, v[146:147]
	v_lshl_add_u64 v[144:145], s[12:13], 0, v[144:145]
	v_bfe_u32 v156, v226, 4, 2
	v_lshlrev_b32_e32 v156, 4, v156
	v_mov_b32_e32 v157, 0
	v_lshl_add_u64 v[144:145], v[144:145], 0, v[156:157]
	s_mov_b64 s[98:99], 0x2000
	v_lshl_add_u64 v[222:223], v[144:145], 0, s[98:99]
	global_load_dwordx4 v[180:183], v[222:223], off offset:2048
	global_load_dwordx4 v[184:187], v[222:223], off offset:3072
	s_and_b64 vcc, exec, s[16:17]
	s_cbranch_vccz .LBB0_1543
	s_barrier
